# P0 off-load variant: slot transposes w_in_b/w_out_b only (5 items per wave), w_out_a back in P0
# baseline (speedup 1.0000x reference)
; #define LAS __attribute__((address_space(3)))
; DI void phase_p0(const Params& p, LAS unsigned char* lds, int gw, int NGW, int wave, int lane) {
;     LAS float* scr = (LAS float*)(lds + wave * 16896);
;     constexpr int I_INA = (D / 128) * (NA / 32), I_OUT = (D / 128) * (D / 32), I_INB = (D / 128) * (NB / 32);
;     constexpr int NITEMS = 2 * (I_INA + I_OUT + I_INB + I_OUT);
;     for (int it = gw; it < NITEMS; it += NGW) {
;         int r = it;
;         if (r < 2 * I_INA) { const int j = r / I_INA; p0_transpose_item(p.w_in_a + (size_t)j * D * NA, D, NA, (bf16_t*)(p.ws + WS_W + j * WPAIR + WO_INA), scr, r % I_INA, lane); continue; } r -= 2 * I_INA;
;         if (r < 2 * I_OUT) { const int j = r / I_OUT; p0_transpose_item(p.w_out_a + (size_t)j * D * D, D, D, (bf16_t*)(p.ws + WS_W + j * WPAIR + WO_OUTA), scr, r % I_OUT, lane); continue; } r -= 2 * I_OUT;
;         if (r < 2 * I_INB) { const int j = r / I_INB; p0_transpose_item(p.w_in_b + (size_t)j * D * NB, D, NB, (bf16_t*)(p.ws + WS_W + j * WPAIR + WO_INB), scr, r % I_INB, lane); continue; } r -= 2 * I_INB;
;         { const int j = r / I_OUT; p0_transpose_item(p.w_out_b + (size_t)j * D * D, D, D, (bf16_t*)(p.ws + WS_W + j * WPAIR + WO_OUTB), scr, r % I_OUT, lane); }
;     }
_Z10hybrid_fwd6Params:
	s_mov_b32 s100, 0
	s_movk_i32 s101, 0x19ff
	v_writelane_b32 v245, s0, 0
	v_writelane_b32 v245, s1, 1
	s_load_dwordx8 s[88:95], s[0:1], 0x40
	s_load_dword s99, s[0:1], 0x68
	s_add_u32 s6, s0, 0x68
	v_and_b32_e32 v34, 0x3ff, v0
	s_addc_u32 s7, s1, 0
	v_readfirstlane_b32 s16, v34
	v_cmp_gt_u32_e32 vcc, 2, v34
	s_and_saveexec_b64 s[8:9], vcc
	v_lshl_add_u32 v1, v34, 2, 0
	v_add_u32_e32 v1, 0x24000, v1
	v_mov_b32_e32 v2, 0
	ds_write_b32 v1, v2
	s_or_b64 exec, exec, s[8:9]
	s_waitcnt lgkmcnt(0)
	s_add_u32 s96, s94, 0x1c900000
	s_addc_u32 s97, s95, 0
	s_cmp_lg_u32 s2, 0
	s_mov_b32 s8, 0
	s_cbranch_scc1 .LBB0_14
	v_sub_u32_e32 v1, 0xd7f, v34
	v_lshrrev_b32_e32 v4, 9, v1
	v_add_u32_e32 v1, 2, v4
	v_add_u32_e32 v3, 0x200, v34
	v_mov_b32_e32 v2, v34
	v_and_b32_e32 v10, 14, v1
	v_mov_b32_e32 v5, v4
	v_mov_b32_e32 v1, v34
	s_mov_b64 s[10:11], 0
	s_mov_b32 s9, 1
	v_mov_b32_e32 v7, 0
	s_mov_b32 s12, s8
	v_mov_b64_e32 v[8:9], v[2:3]
	s_branch .LBB0_5

; DI void phase_p0(const Params& p, LAS unsigned char* lds, int gw, int NGW, int wave, int lane) {
;     ...
;     for (int it = gw; it < NITEMS; it += NGW) {
;         int r = it;
;         if (r < 2 * I_INA) { const int j = r / I_INA; p0_transpose_item(p.w_in_a + (size_t)j * D * NA, D, NA, (bf16_t*)(p.ws + WS_W + j * WPAIR + WO_INA), scr, r % I_INA, lane); continue; } r -= 2 * I_INA;
.LBB0_14:
	s_load_dwordx16 s[72:87], s[0:1], 0x0
	s_lshr_b32 s1, s16, 6
	s_lshl_b32 s0, s2, 3
	s_add_i32 s4, s1, s0
	s_lshl_b32 s0, s99, 3
	s_cmpk_gt_i32 s4, 0x19ff
	v_and_b32_e32 v1, 63, v34
	v_writelane_b32 v239, s2, 0
	s_cbranch_scc1 .LBB0_29

; DI void phase_p0(const Params& p, LAS unsigned char* lds, int gw, int NGW, int wave, int lane) {
;     ...
;     bf16_t* hb = (bf16_t*)(p.ws + WS_HB);
;     { unsigned char* zb = p.ws + WS_Z;
;       for (size_t i = (size_t)(gw * 64 + lane) * 16; i < (size_t)(18 + 32) << 17; i += (size_t)NGW * 64 * 16) {
;           unsigned char* dst = i < ((size_t)18 << 17) ? zb + ((size_t)(64 * 18) << 17) + i : zb + ((size_t)(64 * 32) << 17) + (i - ((size_t)18 << 17));
;           *(u32x4*)dst = (u32x4){0u, 0u, 0u, 0u}; } }
.LBB0_29:
	s_cmpk_lg_i32 s101, 0x19ff
	s_cbranch_scc1 .Lslot_ret
	v_lshl_or_b32 v2, s4, 6, v1
	v_ashrrev_i32_e32 v3, 31, v2
	v_lshlrev_b64 v[2:3], 4, v[2:3]
	s_mov_b64 s[8:9], 0x640000
	v_cmp_gt_u64_e32 vcc, s[8:9], v[2:3]
	s_and_saveexec_b64 s[8:9], vcc
	s_cbranch_execz .LBB0_32
	s_ashr_i32 s1, s0, 31
	v_mov_b32_e32 v5, 0
	s_lshl_b64 s[10:11], s[0:1], 10
	s_mov_b64 s[12:13], 0
	s_mov_b64 s[14:15], 0x240000
	v_mov_b32_e32 v6, 0x1c2c0000
	v_mov_b32_e32 v7, 0x15500000
	v_mov_b32_e32 v8, v5
	v_mov_b32_e32 v9, v5
	v_mov_b32_e32 v10, v5
	v_mov_b32_e32 v11, v5
	s_mov_b64 s[16:17], 0x63ffff

; #define PHASE_IDS() int lane = lane_id_fresh(); int wave = wave_s; asm volatile("" : "+s"(wave)); \
;         int bid = blockIdx.x; asm volatile("" : "+s"(bid)); int G = gridDim.x; asm volatile("" : "+s"(G)); \
;         const int tid = wave * 64 + lane, gw = bid * NWAVES + wave, NGW = G * NWAVES; (void)tid; (void)gw; (void)NGW
; DI void phase_p0(const Params& p, LAS unsigned char* lds, int gw, int NGW, int wave, int lane) {
;     ...
;     for (int it = gw; it < NITEMS; it += NGW) {
;         int r = it;
;         if (r < 2 * I_INA) { const int j = r / I_INA; p0_transpose_item(p.w_in_a + (size_t)j * D * NA, D, NA, (bf16_t*)(p.ws + WS_W + j * WPAIR + WO_INA), scr, r % I_INA, lane); continue; } r -= 2 * I_INA;
;         if (r < 2 * I_OUT) { const int j = r / I_OUT; p0_transpose_item(p.w_out_a + (size_t)j * D * D, D, D, (bf16_t*)(p.ws + WS_W + j * WPAIR + WO_OUTA), scr, r % I_OUT, lane); continue; } r -= 2 * I_OUT;
;         if (r < 2 * I_INB) { const int j = r / I_INB; p0_transpose_item(p.w_in_b + (size_t)j * D * NB, D, NB, (bf16_t*)(p.ws + WS_W + j * WPAIR + WO_INB), scr, r % I_INB, lane); continue; } r -= 2 * I_INB;
;         { const int j = r / I_OUT; p0_transpose_item(p.w_out_b + (size_t)j * D * D, D, D, (bf16_t*)(p.ws + WS_W + j * WPAIR + WO_OUTB), scr, r % I_OUT, lane); }
;     }
; __global__ void __launch_bounds__(NTHREADS) hybrid_fwd(Params p) {
;     ...
;             PHASE_IDS();
;             const int N = isA ? NA : NB;
;             const bf16_t* wt = isA ? (const bf16_t*)(p.ws + WS_W + j * WPAIR + WO_INA) : (const bf16_t*)(p.ws + WS_W + j * WPAIR + WO_INB);
;             pg8::StaticOrder S; S.init(SEQ, N, G, bid);
;             pg8::Gemm g{hb, wt, SEQ, N, D, D, 0};
;             pg8::EpiBf16 E{z, 0, N / 256}; pg8::gemm_phase<pg8::EpiBf16>(lds, g, S, E, tid);
;             meta_gemm<false>(hb + (size_t)SEQ * D, D, wt, N, z, 0, N / 256, lds, bid, G, wave, lane);
.LBB0_74:
	s_bitcmp1_b32 s20, 0
	s_cbranch_scc1 .Lslot_skip
	v_readlane_b32 s4, v239, 0
	s_cmpk_lt_u32 s4, 0x80
	s_cbranch_scc1 .Lslot_skip
	s_waitcnt vmcnt(0) lgkmcnt(0)
	s_barrier
	v_writelane_b32 v246, s0, 0
	v_writelane_b32 v246, s1, 1
	v_writelane_b32 v246, s2, 2
	v_writelane_b32 v246, s3, 3
	v_writelane_b32 v246, s4, 4
	v_writelane_b32 v246, s5, 5
	v_writelane_b32 v246, s6, 6
	v_writelane_b32 v246, s7, 7
	v_writelane_b32 v246, s8, 8
	v_writelane_b32 v246, s9, 9
	v_writelane_b32 v246, s10, 10
	v_writelane_b32 v246, s11, 11
	v_writelane_b32 v246, s12, 12
	v_writelane_b32 v246, s13, 13
	v_writelane_b32 v246, s14, 14
	v_writelane_b32 v246, s15, 15
	v_writelane_b32 v246, s16, 16
	v_writelane_b32 v246, s17, 17
	v_writelane_b32 v246, s18, 18
	v_writelane_b32 v246, s19, 19
	v_writelane_b32 v246, s20, 20
	v_writelane_b32 v246, s21, 21
	v_writelane_b32 v246, s22, 22
	v_writelane_b32 v246, s23, 23
	v_writelane_b32 v246, s24, 24
	v_writelane_b32 v246, s25, 25
	v_writelane_b32 v246, s26, 26
	v_writelane_b32 v246, s27, 27
	v_writelane_b32 v246, s28, 28
	v_writelane_b32 v246, s29, 29
	v_writelane_b32 v246, s30, 30
	v_writelane_b32 v246, s31, 31
	v_writelane_b32 v246, s32, 32
	v_writelane_b32 v246, s33, 33
	v_writelane_b32 v246, s34, 34
	v_writelane_b32 v246, s35, 35
	v_writelane_b32 v246, s36, 36
	v_writelane_b32 v246, s37, 37
	v_writelane_b32 v246, s38, 38
	v_writelane_b32 v246, s39, 39
	v_writelane_b32 v246, s40, 40
	v_writelane_b32 v246, s41, 41
	v_writelane_b32 v246, s42, 42
	v_writelane_b32 v246, s43, 43
	v_writelane_b32 v246, s44, 44
	v_writelane_b32 v246, s45, 45
	v_writelane_b32 v246, s46, 46
	v_writelane_b32 v246, s47, 47
	v_writelane_b32 v246, s48, 48
	v_writelane_b32 v246, s49, 49
	v_writelane_b32 v246, s50, 50
	v_writelane_b32 v246, s51, 51
	v_writelane_b32 v246, s52, 52
	v_writelane_b32 v246, s53, 53
	v_writelane_b32 v246, s54, 54
	v_writelane_b32 v246, s55, 55
	v_writelane_b32 v246, s56, 56
	v_writelane_b32 v246, s57, 57
	v_writelane_b32 v246, s58, 58
	v_writelane_b32 v246, s59, 59
	v_writelane_b32 v246, s60, 60
	v_writelane_b32 v246, s61, 61
	v_writelane_b32 v246, s62, 62
	v_writelane_b32 v246, s63, 63
	v_writelane_b32 v247, s64, 0
	v_writelane_b32 v247, s65, 1
	v_writelane_b32 v247, s66, 2
	v_writelane_b32 v247, s67, 3
	v_writelane_b32 v247, s68, 4
	v_writelane_b32 v247, s69, 5
	v_writelane_b32 v247, s70, 6
	v_writelane_b32 v247, s71, 7
	v_writelane_b32 v247, s72, 8
	v_writelane_b32 v247, s73, 9
	v_writelane_b32 v247, s74, 10
	v_writelane_b32 v247, s75, 11
	v_writelane_b32 v247, s76, 12
	v_writelane_b32 v247, s77, 13
	v_writelane_b32 v247, s78, 14
	v_writelane_b32 v247, s79, 15
	v_writelane_b32 v247, s80, 16
	v_writelane_b32 v247, s81, 17
	v_writelane_b32 v247, s82, 18
	v_writelane_b32 v247, s83, 19
	v_writelane_b32 v247, s84, 20
	v_writelane_b32 v247, s85, 21
	v_writelane_b32 v247, s86, 22
	v_writelane_b32 v247, s87, 23
	v_writelane_b32 v247, s88, 24
	v_writelane_b32 v247, s89, 25
	v_writelane_b32 v247, s90, 26
	v_writelane_b32 v247, s91, 27
	v_writelane_b32 v247, s92, 28
	v_writelane_b32 v247, s93, 29
	v_writelane_b32 v247, s94, 30
	v_writelane_b32 v247, s95, 31
	v_writelane_b32 v247, s96, 32
	v_writelane_b32 v247, s97, 33
	v_writelane_b32 v247, s98, 34
	v_writelane_b32 v247, s99, 35
	v_writelane_b32 v247, vcc_lo, 36
	v_writelane_b32 v247, vcc_hi, 37
	v_readlane_b32 s89, v239, 0
	v_readlane_b32 s91, v239, 1
	v_readlane_b32 s92, v245, 0
	v_readlane_b32 s93, v245, 1
	s_lshr_b32 s90, s20, 1
	s_sub_i32 s89, s89, 0x80
	s_lshl_b32 s89, s89, 3
	s_add_i32 s89, s89, s91
	s_nop 4
	s_load_dwordx16 s[72:87], s[92:93], 0x0
	s_mov_b32 s88, 1
	s_waitcnt lgkmcnt(0)
